# final scan config plus: producer skips parts C/D/E in the pipeline-drain iterations (it >= nsteps), where the clamped chunk it would re-produce is never consumed
# baseline (speedup 1.0000x reference)
.LBB0_295:
	ds_read_b128 v[130:133], v188
	ds_read_b128 v[134:137], v188 offset:16
	ds_read_b128 v[138:141], v188 offset:256
	ds_read_b128 v[142:145], v188 offset:272
	ds_read_b128 v[146:149], v188 offset:512
	ds_read_b128 v[150:153], v188 offset:528
	ds_read_b128 v[154:157], v188 offset:768
	ds_read_b128 v[166:169], v188 offset:784
	s_sub_i32 s0, s8, s25
	v_cmp_gt_i32_e32 vcc, s26, v175
	s_min_i32 s1, s24, s20
	s_lshl_b32 s1, s1, 5
	s_sub_i32 s25, s17, s1
	v_lshlrev_b32_e32 v172, 16, v126
	v_and_b32_e32 v173, 0xffff0000, v126
	s_cmp_gt_i32 s25, 31
	s_waitcnt lgkmcnt(6)
	v_mul_f32_e32 v238, v130, v130
	v_mul_f32_e32 v239, v131, v131
	v_mul_f32_e32 v240, v132, v132
	v_mul_f32_e32 v241, v133, v133
	v_fmac_f32_e32 v238, v134, v134
	v_fmac_f32_e32 v239, v135, v135
	v_fmac_f32_e32 v240, v136, v136
	v_fmac_f32_e32 v241, v137, v137
	s_waitcnt lgkmcnt(4)
	v_fmac_f32_e32 v238, v138, v138
	v_fmac_f32_e32 v239, v139, v139
	v_fmac_f32_e32 v240, v140, v140
	v_fmac_f32_e32 v241, v141, v141
	v_fmac_f32_e32 v238, v142, v142
	v_fmac_f32_e32 v239, v143, v143
	v_fmac_f32_e32 v240, v144, v144
	v_fmac_f32_e32 v241, v145, v145
	s_waitcnt lgkmcnt(2)
	v_fmac_f32_e32 v238, v146, v146
	v_fmac_f32_e32 v239, v147, v147
	v_fmac_f32_e32 v240, v148, v148
	v_fmac_f32_e32 v241, v149, v149
	v_fmac_f32_e32 v238, v150, v150
	v_fmac_f32_e32 v239, v151, v151
	v_fmac_f32_e32 v240, v152, v152
	v_fmac_f32_e32 v241, v153, v153
	s_waitcnt lgkmcnt(0)
	v_fmac_f32_e32 v238, v154, v154
	v_fmac_f32_e32 v239, v155, v155
	v_fmac_f32_e32 v240, v156, v156
	v_fmac_f32_e32 v241, v157, v157
	v_fmac_f32_e32 v238, v166, v166
	v_fmac_f32_e32 v239, v167, v167
	v_fmac_f32_e32 v240, v168, v168
	v_fmac_f32_e32 v241, v169, v169
	v_add_f32_e32 v238, v238, v239
	v_add_f32_e32 v240, v240, v241
	v_add_f32_e32 v158, v238, v240
	s_nop 1
	v_add_f32_dpp v158, v158, v158 quad_perm:[1,0,3,2] row_mask:0xf bank_mask:0xf
	s_nop 1
	v_add_f32_dpp v158, v158, v158 quad_perm:[2,3,0,1] row_mask:0xf bank_mask:0xf
	s_nop 1
	v_add_f32_dpp v158, v158, v158 row_half_mirror row_mask:0xf bank_mask:0xf
	v_fmamk_f32 v158, v158, 0x3b800000, v206
	v_rsq_f32_e32 v158, v158
	s_waitcnt vmcnt(58)
	v_mov_b32_e32 v159, s0
	v_cndmask_b32_e32 v159, v210, v159, vcc
	v_add_u32_e32 v170, v159, v175
	v_ashrrev_i32_e32 v171, 31, v170
	v_lshlrev_b64 v[170:171], 13, v[170:171]
	v_lshl_add_u64 v[170:171], v[74:75], 0, v[170:171]
	v_pk_mul_f32 v[130:131], v[130:131], v[158:159] op_sel_hi:[1,0]
	v_lshlrev_b32_e32 v238, 16, v80
	v_and_b32_e32 v239, 0xffff0000, v80
	v_pk_mul_f32 v[130:131], v[130:131], v[238:239]
	v_cvt_pk_bf16_f32 v80, v130, v131
	v_pk_mul_f32 v[132:133], v[132:133], v[158:159] op_sel_hi:[1,0]
	v_lshlrev_b32_e32 v238, 16, v81
	v_and_b32_e32 v239, 0xffff0000, v81
	v_pk_mul_f32 v[132:133], v[132:133], v[238:239]
	v_cvt_pk_bf16_f32 v81, v132, v133
	v_pk_mul_f32 v[134:135], v[134:135], v[158:159] op_sel_hi:[1,0]
	v_lshlrev_b32_e32 v238, 16, v82
	v_and_b32_e32 v239, 0xffff0000, v82
	v_pk_mul_f32 v[134:135], v[134:135], v[238:239]
	v_cvt_pk_bf16_f32 v82, v134, v135
	v_pk_mul_f32 v[136:137], v[136:137], v[158:159] op_sel_hi:[1,0]
	v_lshlrev_b32_e32 v238, 16, v83
	v_and_b32_e32 v239, 0xffff0000, v83
	v_pk_mul_f32 v[136:137], v[136:137], v[238:239]
	v_cvt_pk_bf16_f32 v83, v136, v137
	global_store_dwordx4 v[170:171], v[80:83], off
	v_pk_mul_f32 v[138:139], v[138:139], v[158:159] op_sel_hi:[1,0]
	v_lshlrev_b32_e32 v238, 16, v84
	v_and_b32_e32 v239, 0xffff0000, v84
	v_pk_mul_f32 v[138:139], v[138:139], v[238:239]
	v_cvt_pk_bf16_f32 v84, v138, v139
	v_pk_mul_f32 v[140:141], v[140:141], v[158:159] op_sel_hi:[1,0]
	v_lshlrev_b32_e32 v238, 16, v85
	v_and_b32_e32 v239, 0xffff0000, v85
	v_pk_mul_f32 v[140:141], v[140:141], v[238:239]
	v_cvt_pk_bf16_f32 v85, v140, v141
	v_pk_mul_f32 v[142:143], v[142:143], v[158:159] op_sel_hi:[1,0]
	v_lshlrev_b32_e32 v238, 16, v86
	v_and_b32_e32 v239, 0xffff0000, v86
	v_pk_mul_f32 v[142:143], v[142:143], v[238:239]
	v_cvt_pk_bf16_f32 v86, v142, v143
	v_pk_mul_f32 v[144:145], v[144:145], v[158:159] op_sel_hi:[1,0]
	v_lshlrev_b32_e32 v238, 16, v87
	v_and_b32_e32 v239, 0xffff0000, v87
	v_pk_mul_f32 v[144:145], v[144:145], v[238:239]
	v_cvt_pk_bf16_f32 v87, v144, v145
	global_store_dwordx4 v[170:171], v[84:87], off offset:128
	v_pk_mul_f32 v[146:147], v[146:147], v[158:159] op_sel_hi:[1,0]
	v_lshlrev_b32_e32 v238, 16, v92
	v_and_b32_e32 v239, 0xffff0000, v92
	v_pk_mul_f32 v[146:147], v[146:147], v[238:239]
	v_cvt_pk_bf16_f32 v92, v146, v147
	v_pk_mul_f32 v[148:149], v[148:149], v[158:159] op_sel_hi:[1,0]
	v_lshlrev_b32_e32 v238, 16, v93
	v_and_b32_e32 v239, 0xffff0000, v93
	v_pk_mul_f32 v[148:149], v[148:149], v[238:239]
	v_cvt_pk_bf16_f32 v93, v148, v149
	v_pk_mul_f32 v[150:151], v[150:151], v[158:159] op_sel_hi:[1,0]
	v_lshlrev_b32_e32 v238, 16, v94
	v_and_b32_e32 v239, 0xffff0000, v94
	v_pk_mul_f32 v[150:151], v[150:151], v[238:239]
	v_cvt_pk_bf16_f32 v94, v150, v151
	v_pk_mul_f32 v[152:153], v[152:153], v[158:159] op_sel_hi:[1,0]
	v_lshlrev_b32_e32 v238, 16, v95
	v_and_b32_e32 v239, 0xffff0000, v95
	v_pk_mul_f32 v[152:153], v[152:153], v[238:239]
	v_cvt_pk_bf16_f32 v95, v152, v153
	global_store_dwordx4 v[170:171], v[92:95], off offset:256
	v_pk_mul_f32 v[154:155], v[154:155], v[158:159] op_sel_hi:[1,0]
	v_lshlrev_b32_e32 v238, 16, v96
	v_and_b32_e32 v239, 0xffff0000, v96
	v_pk_mul_f32 v[154:155], v[154:155], v[238:239]
	v_cvt_pk_bf16_f32 v96, v154, v155
	v_pk_mul_f32 v[156:157], v[156:157], v[158:159] op_sel_hi:[1,0]
	v_lshlrev_b32_e32 v238, 16, v97
	v_and_b32_e32 v239, 0xffff0000, v97
	v_pk_mul_f32 v[156:157], v[156:157], v[238:239]
	v_cvt_pk_bf16_f32 v97, v156, v157
	v_pk_mul_f32 v[166:167], v[166:167], v[158:159] op_sel_hi:[1,0]
	v_lshlrev_b32_e32 v238, 16, v98
	v_and_b32_e32 v239, 0xffff0000, v98
	v_pk_mul_f32 v[166:167], v[166:167], v[238:239]
	v_cvt_pk_bf16_f32 v98, v166, v167
	v_pk_mul_f32 v[168:169], v[168:169], v[158:159] op_sel_hi:[1,0]
	v_lshlrev_b32_e32 v238, 16, v99
	v_and_b32_e32 v239, 0xffff0000, v99
	v_pk_mul_f32 v[168:169], v[168:169], v[238:239]
	v_cvt_pk_bf16_f32 v99, v168, v169
	global_store_dwordx4 v[170:171], v[96:99], off offset:384
	s_waitcnt vmcnt(4)
	v_lshlrev_b32_e32 v168, 16, v232
	v_add_u32_e32 v238, s1, v217
	v_ashrrev_i32_e32 v239, 31, v238
	v_lshlrev_b64 v[238:239], 13, v[238:239]
	v_lshl_add_u64 v[238:239], v[78:79], 0, v[238:239]
	global_load_dwordx4 v[80:83], v[238:239], off
	global_load_dwordx4 v[84:87], v[238:239], off offset:128
	global_load_dwordx4 v[92:95], v[238:239], off offset:256
	global_load_dwordx4 v[96:99], v[238:239], off offset:384
	s_cmp_lt_u32 s24, s18
	s_cbranch_scc1 .Lscan_tl_n0
	s_add_i32 s25, s24, 2
	s_mov_b64 s[0:1], exec
	s_waitcnt vmcnt(0)
	s_branch .LBB0_301
.Lscan_tl_n0:
	s_cmp_gt_i32 s25, 31
	s_mov_b64 s[0:1], -1
	v_lshlrev_b32_e32 v170, 16, v234
	v_lshlrev_b32_e32 v166, 16, v231
	v_lshlrev_b32_e32 v158, 16, v229
	s_cbranch_scc1 .LBB0_297
	s_min_i32 s0, s25, 32
	v_add_f32_e32 v130, 0, v106
	v_cmp_gt_i32_e32 vcc, s0, v176
	v_and_b32_e32 v132, 0xffff0000, v235
	v_and_b32_e32 v134, 0xffff0000, v234
	v_cndmask_b32_e32 v136, 0, v130, vcc
	v_add_f32_e32 v130, 0, v107
	v_cndmask_b32_e32 v139, 0, v130, vcc
	v_lshlrev_b32_e32 v130, 16, v233
	v_cndmask_b32_e32 v131, 0, v130, vcc
	v_and_b32_e32 v130, 0xffff0000, v233
	v_cndmask_b32_e32 v241, 0, v130, vcc
	v_cmp_gt_i32_e32 vcc, s0, v1
	v_lshlrev_b32_e32 v130, 16, v235
	v_and_b32_e32 v135, 0xffff0000, v232
	v_cndmask_b32_e32 v133, 0, v102, vcc
	v_add_f32_e32 v138, v136, v133
	v_cndmask_b32_e32 v239, 0, v130, vcc
	v_cndmask_b32_e32 v240, 0, v132, vcc
	v_cndmask_b32_e32 v133, 0, v103, vcc
	v_cmp_gt_i32_e32 vcc, s0, v40
	v_and_b32_e32 v137, 0xffff0000, v231
	v_and_b32_e32 v140, 0xffff0000, v229
	v_cndmask_b32_e32 v132, 0, v118, vcc
	v_cmp_gt_i32_e32 vcc, s0, v41
	v_pk_add_f32 v[146:147], v[132:133], v[138:139]
	v_lshlrev_b32_e32 v159, 16, v236
	v_cndmask_b32_e32 v157, 0, v134, vcc
	v_cndmask_b32_e32 v156, 0, v170, vcc
	v_cndmask_b32_e32 v133, 0, v119, vcc
	v_cmp_gt_i32_e32 vcc, s0, v54
	v_lshlrev_b32_e32 v162, 16, v237
	v_and_b32_e32 v163, 0xffff0000, v236
	v_cndmask_b32_e32 v132, 0, v114, vcc
	v_cmp_gt_i32_e32 vcc, s0, v3
	v_pk_add_f32 v[148:149], v[132:133], v[146:147]
	s_nop 0
	v_cndmask_b32_e32 v155, 0, v135, vcc
	v_cndmask_b32_e32 v154, 0, v168, vcc
	v_cndmask_b32_e32 v133, 0, v115, vcc
	v_cmp_gt_i32_e32 vcc, s0, v52
	s_nop 1
	v_cndmask_b32_e32 v132, 0, v100, vcc
	v_cmp_gt_i32_e32 vcc, s0, v43
	v_pk_add_f32 v[142:143], v[132:133], v[148:149]
	s_nop 0
	v_cndmask_b32_e32 v153, 0, v137, vcc
	v_cndmask_b32_e32 v152, 0, v166, vcc
	v_cndmask_b32_e32 v133, 0, v101, vcc
	v_cmp_gt_i32_e32 vcc, s0, v42
	s_nop 1
	v_cndmask_b32_e32 v132, 0, v90, vcc
	v_cmp_gt_i32_e32 vcc, s0, v51
	v_pk_add_f32 v[144:145], v[132:133], v[142:143]
	s_nop 0
	v_cndmask_b32_e32 v151, 0, v140, vcc
	v_cndmask_b32_e32 v150, 0, v158, vcc
	v_cndmask_b32_e32 v133, 0, v91, vcc
	v_cmp_gt_i32_e32 vcc, s0, v50
	s_nop 1
	v_cndmask_b32_e32 v132, 0, v108, vcc
	v_cmp_gt_i32_e32 vcc, s0, v45
	v_cmp_gt_i32_e64 s[0:1], s0, v44
	v_pk_add_f32 v[140:141], v[132:133], v[144:145]
	v_cndmask_b32_e32 v133, 0, v109, vcc
	v_cndmask_b32_e64 v132, 0, v128, s[0:1]
	v_cndmask_b32_e32 v130, 0, v159, vcc
	v_pk_add_f32 v[134:135], v[132:133], v[140:141]
	v_cndmask_b32_e64 v132, 0, v129, s[0:1]
	v_and_b32_e32 v159, 0xffff0000, v237
	v_add_f32_e32 v137, v132, v135
	v_cndmask_b32_e32 v133, 0, v163, vcc
	v_cndmask_b32_e64 v132, 0, v162, s[0:1]
	v_cndmask_b32_e64 v238, 0, v159, s[0:1]
	s_mov_b64 s[0:1], 0

.LBB0_305:
	ds_read_b128 v[130:133], v188 offset:33280
	ds_read_b128 v[134:137], v188 offset:33296
	ds_read_b128 v[138:141], v188 offset:33536
	ds_read_b128 v[142:145], v188 offset:33552
	ds_read_b128 v[146:149], v188 offset:33792
	ds_read_b128 v[150:153], v188 offset:33808
	ds_read_b128 v[154:157], v188 offset:34048
	ds_read_b128 v[166:169], v188 offset:34064
	s_sub_i32 s0, s21, s0
	v_cmp_gt_i32_e32 vcc, s1, v175
	s_add_i32 s10, s24, 1
	s_min_i32 s10, s10, s20
	v_lshlrev_b32_e32 v170, 16, v124
	v_and_b32_e32 v171, 0xffff0000, v124
	s_lshl_b32 s10, s10, 5
	s_waitcnt lgkmcnt(6)
	v_mul_f32_e32 v238, v130, v130
	v_mul_f32_e32 v239, v131, v131
	v_mul_f32_e32 v240, v132, v132
	v_mul_f32_e32 v241, v133, v133
	v_fmac_f32_e32 v238, v134, v134
	v_fmac_f32_e32 v239, v135, v135
	v_fmac_f32_e32 v240, v136, v136
	v_fmac_f32_e32 v241, v137, v137
	s_waitcnt lgkmcnt(4)
	v_fmac_f32_e32 v238, v138, v138
	v_fmac_f32_e32 v239, v139, v139
	v_fmac_f32_e32 v240, v140, v140
	v_fmac_f32_e32 v241, v141, v141
	v_fmac_f32_e32 v238, v142, v142
	v_fmac_f32_e32 v239, v143, v143
	v_fmac_f32_e32 v240, v144, v144
	v_fmac_f32_e32 v241, v145, v145
	s_waitcnt lgkmcnt(2)
	v_fmac_f32_e32 v238, v146, v146
	v_fmac_f32_e32 v239, v147, v147
	v_fmac_f32_e32 v240, v148, v148
	v_fmac_f32_e32 v241, v149, v149
	v_fmac_f32_e32 v238, v150, v150
	v_fmac_f32_e32 v239, v151, v151
	v_fmac_f32_e32 v240, v152, v152
	v_fmac_f32_e32 v241, v153, v153
	s_waitcnt lgkmcnt(0)
	v_fmac_f32_e32 v238, v154, v154
	v_fmac_f32_e32 v239, v155, v155
	v_fmac_f32_e32 v240, v156, v156
	v_fmac_f32_e32 v241, v157, v157
	v_fmac_f32_e32 v238, v166, v166
	v_fmac_f32_e32 v239, v167, v167
	v_fmac_f32_e32 v240, v168, v168
	v_fmac_f32_e32 v241, v169, v169
	v_add_f32_e32 v238, v238, v239
	v_add_f32_e32 v240, v240, v241
	v_add_f32_e32 v158, v238, v240
	s_nop 1
	v_add_f32_dpp v158, v158, v158 quad_perm:[1,0,3,2] row_mask:0xf bank_mask:0xf
	s_nop 1
	v_add_f32_dpp v158, v158, v158 quad_perm:[2,3,0,1] row_mask:0xf bank_mask:0xf
	s_nop 1
	v_add_f32_dpp v158, v158, v158 row_half_mirror row_mask:0xf bank_mask:0xf
	v_fmamk_f32 v158, v158, 0x3b800000, v206
	v_rsq_f32_e32 v158, v158
	s_waitcnt vmcnt(56)
	v_mov_b32_e32 v159, s0
	v_cndmask_b32_e32 v159, v210, v159, vcc
	v_add_u32_e32 v162, v159, v175
	v_ashrrev_i32_e32 v163, 31, v162
	v_lshlrev_b64 v[162:163], 13, v[162:163]
	v_lshl_add_u64 v[162:163], v[74:75], 0, v[162:163]
	s_mov_b64 s[0:1], -1
	v_pk_mul_f32 v[130:131], v[130:131], v[158:159] op_sel_hi:[1,0]
	v_lshlrev_b32_e32 v238, 16, v120
	v_and_b32_e32 v239, 0xffff0000, v120
	v_pk_mul_f32 v[130:131], v[130:131], v[238:239]
	v_cvt_pk_bf16_f32 v120, v130, v131
	v_pk_mul_f32 v[132:133], v[132:133], v[158:159] op_sel_hi:[1,0]
	v_lshlrev_b32_e32 v238, 16, v121
	v_and_b32_e32 v239, 0xffff0000, v121
	v_pk_mul_f32 v[132:133], v[132:133], v[238:239]
	v_cvt_pk_bf16_f32 v121, v132, v133
	v_pk_mul_f32 v[134:135], v[134:135], v[158:159] op_sel_hi:[1,0]
	v_lshlrev_b32_e32 v238, 16, v122
	v_and_b32_e32 v239, 0xffff0000, v122
	v_pk_mul_f32 v[134:135], v[134:135], v[238:239]
	v_cvt_pk_bf16_f32 v122, v134, v135
	v_pk_mul_f32 v[136:137], v[136:137], v[158:159] op_sel_hi:[1,0]
	v_lshlrev_b32_e32 v238, 16, v123
	v_and_b32_e32 v239, 0xffff0000, v123
	v_pk_mul_f32 v[136:137], v[136:137], v[238:239]
	v_cvt_pk_bf16_f32 v123, v136, v137
	global_store_dwordx4 v[162:163], v[120:123], off
	v_pk_mul_f32 v[138:139], v[138:139], v[158:159] op_sel_hi:[1,0]
	v_lshlrev_b32_e32 v238, 16, v124
	v_and_b32_e32 v239, 0xffff0000, v124
	v_pk_mul_f32 v[138:139], v[138:139], v[238:239]
	v_cvt_pk_bf16_f32 v124, v138, v139
	v_pk_mul_f32 v[140:141], v[140:141], v[158:159] op_sel_hi:[1,0]
	v_lshlrev_b32_e32 v238, 16, v125
	v_and_b32_e32 v239, 0xffff0000, v125
	v_pk_mul_f32 v[140:141], v[140:141], v[238:239]
	v_cvt_pk_bf16_f32 v125, v140, v141
	v_pk_mul_f32 v[142:143], v[142:143], v[158:159] op_sel_hi:[1,0]
	v_lshlrev_b32_e32 v238, 16, v126
	v_and_b32_e32 v239, 0xffff0000, v126
	v_pk_mul_f32 v[142:143], v[142:143], v[238:239]
	v_cvt_pk_bf16_f32 v126, v142, v143
	v_pk_mul_f32 v[144:145], v[144:145], v[158:159] op_sel_hi:[1,0]
	v_lshlrev_b32_e32 v238, 16, v127
	v_and_b32_e32 v239, 0xffff0000, v127
	v_pk_mul_f32 v[144:145], v[144:145], v[238:239]
	v_cvt_pk_bf16_f32 v127, v144, v145
	global_store_dwordx4 v[162:163], v[124:127], off offset:128
	v_pk_mul_f32 v[146:147], v[146:147], v[158:159] op_sel_hi:[1,0]
	v_lshlrev_b32_e32 v238, 16, v110
	v_and_b32_e32 v239, 0xffff0000, v110
	v_pk_mul_f32 v[146:147], v[146:147], v[238:239]
	v_cvt_pk_bf16_f32 v110, v146, v147
	v_pk_mul_f32 v[148:149], v[148:149], v[158:159] op_sel_hi:[1,0]
	v_lshlrev_b32_e32 v238, 16, v111
	v_and_b32_e32 v239, 0xffff0000, v111
	v_pk_mul_f32 v[148:149], v[148:149], v[238:239]
	v_cvt_pk_bf16_f32 v111, v148, v149
	v_pk_mul_f32 v[150:151], v[150:151], v[158:159] op_sel_hi:[1,0]
	v_lshlrev_b32_e32 v238, 16, v112
	v_and_b32_e32 v239, 0xffff0000, v112
	v_pk_mul_f32 v[150:151], v[150:151], v[238:239]
	v_cvt_pk_bf16_f32 v112, v150, v151
	v_pk_mul_f32 v[152:153], v[152:153], v[158:159] op_sel_hi:[1,0]
	v_lshlrev_b32_e32 v238, 16, v113
	v_and_b32_e32 v239, 0xffff0000, v113
	v_pk_mul_f32 v[152:153], v[152:153], v[238:239]
	v_cvt_pk_bf16_f32 v113, v152, v153
	global_store_dwordx4 v[162:163], v[110:113], off offset:256
	v_pk_mul_f32 v[154:155], v[154:155], v[158:159] op_sel_hi:[1,0]
	v_lshlrev_b32_e32 v238, 16, v88
	v_and_b32_e32 v239, 0xffff0000, v88
	v_pk_mul_f32 v[154:155], v[154:155], v[238:239]
	v_cvt_pk_bf16_f32 v88, v154, v155
	v_pk_mul_f32 v[156:157], v[156:157], v[158:159] op_sel_hi:[1,0]
	v_lshlrev_b32_e32 v238, 16, v89
	v_and_b32_e32 v239, 0xffff0000, v89
	v_pk_mul_f32 v[156:157], v[156:157], v[238:239]
	v_cvt_pk_bf16_f32 v89, v156, v157
	v_pk_mul_f32 v[166:167], v[166:167], v[158:159] op_sel_hi:[1,0]
	v_lshlrev_b32_e32 v238, 16, v116
	v_and_b32_e32 v239, 0xffff0000, v116
	v_pk_mul_f32 v[166:167], v[166:167], v[238:239]
	v_cvt_pk_bf16_f32 v116, v166, v167
	v_pk_mul_f32 v[168:169], v[168:169], v[158:159] op_sel_hi:[1,0]
	v_lshlrev_b32_e32 v238, 16, v117
	v_and_b32_e32 v239, 0xffff0000, v117
	v_pk_mul_f32 v[168:169], v[168:169], v[238:239]
	v_cvt_pk_bf16_f32 v117, v168, v169
	global_store_dwordx2 v[162:163], v[88:89], off offset:384
	global_store_dwordx2 v[162:163], v[116:117], off offset:392
	v_add_u32_e32 v238, s10, v217
	v_ashrrev_i32_e32 v239, 31, v238
	v_lshlrev_b64 v[238:239], 13, v[238:239]
	v_lshl_add_u64 v[238:239], v[78:79], 0, v[238:239]
	global_load_dwordx4 v[120:123], v[238:239], off
	global_load_dwordx4 v[124:127], v[238:239], off offset:128
	global_load_dwordx4 v[110:113], v[238:239], off offset:256
	global_load_dwordx2 v[88:89], v[238:239], off offset:384
	global_load_dwordx2 v[116:117], v[238:239], off offset:392
	s_add_i32 s98, s24, 1
	s_cmp_lt_u32 s98, s18
	s_cbranch_scc1 .Lscan_tl_n1
	s_mov_b64 s[0:1], exec
	s_waitcnt vmcnt(0)
	s_branch .LBB0_290
.Lscan_tl_n1:
	s_sub_i32 s10, s17, s10
	s_cmp_gt_i32 s10, 31
	s_cbranch_scc1 .LBB0_307
	s_min_i32 s10, s10, 32
	v_add_f32_e32 v130, 0, v68
	v_cmp_gt_i32_e32 vcc, s10, v176
	v_cmp_gt_i32_e64 s[0:1], s10, v40
	v_and_b32_e32 v133, 0xffff0000, v215
	v_cndmask_b32_e32 v144, 0, v130, vcc
	v_add_f32_e32 v130, 0, v69
	v_cndmask_b32_e32 v143, 0, v130, vcc
	v_lshlrev_b32_e32 v130, 16, v201
	v_cndmask_b32_e32 v141, 0, v130, vcc
	v_and_b32_e32 v130, 0xffff0000, v201
	v_cndmask_b32_e32 v169, 0, v130, vcc
	v_cmp_gt_i32_e32 vcc, s10, v1
	v_lshlrev_b32_e32 v132, 16, v202
	v_cndmask_b32_e64 v138, 0, v132, s[0:1]
	v_cndmask_b32_e32 v130, 0, v104, vcc
	v_add_f32_e32 v142, v144, v130
	v_lshlrev_b32_e32 v130, 16, v215
	v_cndmask_b32_e32 v140, 0, v130, vcc
	v_cndmask_b32_e32 v131, 0, v105, vcc
	v_cndmask_b32_e64 v130, 0, v76, s[0:1]
	v_pk_add_f32 v[146:147], v[130:131], v[142:143]
	v_cndmask_b32_e64 v130, 0, v77, s[0:1]
	v_add_f32_e32 v241, v130, v147
	v_cndmask_b32_e32 v139, 0, v133, vcc
	v_and_b32_e32 v130, 0xffff0000, v202
	v_cmp_gt_i32_e32 vcc, s10, v3
	v_cndmask_b32_e64 v166, 0, v130, s[0:1]
	v_and_b32_e32 v131, 0xffff0000, v197
	v_cndmask_b32_e32 v130, 0, v72, vcc
	v_add_f32_e32 v239, v130, v146
	v_cndmask_b32_e32 v130, 0, v73, vcc
	v_add_f32_e32 v240, v130, v241
	v_lshlrev_b32_e32 v130, 16, v200
	v_cndmask_b32_e32 v135, 0, v130, vcc
	v_and_b32_e32 v130, 0xffff0000, v200
	v_cndmask_b32_e32 v159, 0, v130, vcc
	v_cmp_gt_i32_e32 vcc, s10, v43
	v_cmp_gt_i32_e64 s[0:1], s10, v42
	v_and_b32_e32 v133, 0xffff0000, v196
	v_cndmask_b32_e32 v130, 0, v70, vcc
	v_add_f32_e32 v173, v130, v239
	v_cndmask_b32_e32 v130, 0, v71, vcc
	v_add_f32_e32 v238, v130, v240
	v_lshlrev_b32_e32 v130, 16, v197
	v_cndmask_b32_e32 v134, 0, v130, vcc
	v_lshlrev_b32_e32 v130, 16, v198
	v_cndmask_b32_e64 v132, 0, v62, s[0:1]
	v_cndmask_b32_e32 v137, 0, v131, vcc
	v_cndmask_b32_e64 v136, 0, v130, s[0:1]
	v_and_b32_e32 v130, 0xffff0000, v198
	v_cmp_gt_i32_e32 vcc, s10, v45
	v_add_f32_e32 v171, v132, v173
	v_cndmask_b32_e64 v132, 0, v63, s[0:1]
	v_cndmask_b32_e64 v131, 0, v130, s[0:1]
	v_cndmask_b32_e32 v130, 0, v66, vcc
	v_add_f32_e32 v172, v132, v238
	v_add_f32_e32 v168, v130, v171
	v_cndmask_b32_e32 v130, 0, v67, vcc
	v_cmp_gt_i32_e64 s[0:1], s10, v44
	v_add_f32_e32 v170, v130, v172
	v_lshlrev_b32_e32 v130, 16, v196
	v_cndmask_b32_e64 v148, 0, v65, s[0:1]
	v_lshlrev_b32_e32 v132, 16, v225
	v_cndmask_b32_e64 v145, 0, v64, s[0:1]
	v_add_f32_e32 v167, v148, v170
	v_and_b32_e32 v148, 0xffff0000, v225
	v_cndmask_b32_e32 v130, 0, v130, vcc
	v_add_f32_e32 v145, v145, v168
	v_cndmask_b32_e32 v133, 0, v133, vcc
	v_cndmask_b32_e64 v132, 0, v132, s[0:1]
	v_cndmask_b32_e64 v158, 0, v148, s[0:1]
	s_mov_b64 s[0:1], 0
